# prep: Hyena filter w1 staging loads issued together (five per lane) instead of one load + wait per iteration
# baseline (speedup 1.0000x reference)
.LBB0_17:
	global_load_dword v5, v[2:3], off
	global_load_dword v6, v[2:3], off offset:2048
	v_add_co_u32_e32 v8, vcc, 0x1000, v2
	s_nop 1
	v_addc_co_u32_e32 v9, vcc, 0, v3, vcc
	v_add_co_u32_e32 v10, vcc, 0x2000, v2
	s_nop 1
	v_addc_co_u32_e32 v11, vcc, 0, v3, vcc
	global_load_dword v7, v[8:9], off
	global_load_dword v12, v[8:9], off offset:2048
	v_cmp_gt_u32_e32 vcc, 64, v164
	s_and_saveexec_b64 s[6:7], vcc
	global_load_dword v13, v[10:11], off
	s_mov_b64 exec, s[6:7]
	s_waitcnt vmcnt(0)
	ds_write_b32 v1, v5
	ds_write_b32 v1, v6 offset:2048
	ds_write_b32 v1, v7 offset:4096
	ds_write_b32 v1, v12 offset:6144
	s_and_saveexec_b64 s[6:7], vcc
	ds_write_b32 v1, v13 offset:8192
	s_mov_b64 exec, s[6:7]
	s_or_b64 exec, exec, s[0:1]
	v_mov_b32_e32 v3, 0
	v_mov_b32_e32 v2, v176
	v_lshl_add_u64 v[4:5], s[80:81], 0, v[2:3]
	s_movk_i32 s0, 0x1000
	v_add_co_u32_e32 v6, vcc, s0, v4
	v_lshl_add_u64 v[2:3], s[36:37], 0, v[2:3]
	v_or_b32_e32 v1, 0x1000, v142
	v_addc_co_u32_e32 v7, vcc, 0, v5, vcc
	global_load_dword v8, v176, s[80:81]
	global_load_dword v9, v176, s[36:37]
	global_load_dword v10, v176, s[36:37] offset:2048
	global_load_dword v11, v176, s[80:81] offset:2048
	global_load_dword v12, v1, s[80:81]
	global_load_dword v13, v1, s[36:37]
	global_load_dword v14, v[6:7], off offset:2048
	v_add_co_u32_e32 v6, vcc, s0, v2
	s_movk_i32 s0, 0x2000
	s_nop 0
	v_addc_co_u32_e32 v7, vcc, 0, v3, vcc
	global_load_dword v15, v[6:7], off offset:2048
	v_or_b32_e32 v1, 0x2000, v142
	v_add_co_u32_e32 v6, vcc, s0, v4
	v_or_b32_e32 v19, 0xc00, v164
	global_load_dword v16, v1, s[80:81]
	global_load_dword v17, v1, s[36:37]
	v_addc_co_u32_e32 v7, vcc, 0, v5, vcc
	v_lshlrev_b32_e32 v1, 2, v19
	global_load_dword v18, v[6:7], off offset:2048
	global_load_dword v20, v1, s[80:81]
	v_add_co_u32_e32 v6, vcc, s0, v2
	v_add_u32_e32 v181, 0, v142
	s_nop 0
	v_addc_co_u32_e32 v7, vcc, 0, v3, vcc
	global_load_dword v21, v1, s[36:37]
	s_nop 0
	global_load_dword v6, v[6:7], off offset:2048
	s_movk_i32 s0, 0xe00
	v_add_u32_e32 v1, 0x80, v181
	v_cmp_gt_u32_e32 vcc, s0, v19
	s_waitcnt vmcnt(10)
	ds_write2st64_b32 v1, v8, v11 offset0:53 offset1:61
	s_waitcnt vmcnt(8)
	ds_write2st64_b32 v1, v10, v13 offset0:125 offset1:133
	s_waitcnt vmcnt(2)
	ds_write2st64_b32 v1, v20, v9 offset0:101 offset1:117
	ds_write2st64_b32 v1, v12, v14 offset0:69 offset1:77
	ds_write2st64_b32 v1, v15, v17 offset0:141 offset1:149
	ds_write2st64_b32 v1, v16, v18 offset0:85 offset1:93
	s_waitcnt vmcnt(0)
	ds_write2st64_b32 v1, v6, v21 offset0:157 offset1:165
	s_and_saveexec_b64 s[0:1], vcc
	v_readlane_b32 s76, v255, 11
	s_xor_b64 s[0:1], exec, s[0:1]
	v_readlane_b32 s77, v255, 12
	s_cbranch_execz .LBB0_20
	v_add_co_u32_e32 v4, vcc, 0x3000, v4
	s_nop 1
	v_addc_co_u32_e32 v5, vcc, 0, v5, vcc
	v_add_co_u32_e32 v2, vcc, 0x3000, v2
	global_load_dword v4, v[4:5], off offset:2048
	s_nop 0
	v_addc_co_u32_e32 v3, vcc, 0, v3, vcc
	global_load_dword v2, v[2:3], off offset:2048
	s_waitcnt vmcnt(0)
	ds_write2st64_b32 v1, v4, v2 offset0:109 offset1:173

.LBB0_944:
	s_lshl_b32 s18, s48, 4
	s_mov_b32 s10, 0xffffde00
	s_mov_b32 s11, -1
	s_mov_b32 s20, 0x2200
	s_mov_b32 s21, 0
	global_load_dword v50, v[2:3], off
	global_load_dword v51, v[4:5], off
	global_load_dword v52, v[6:7], off
	global_load_dword v53, v[8:9], off
	v_or_b32_e32 v20, s18, v220
	v_mad_i64_i32 v[22:23], s[0:1], v20, s23, v[14:15]
	v_lshl_add_u64 v[22:23], v[22:23], 0, s[16:17]
	v_lshl_add_u64 v[26:27], v[22:23], 0, v[0:1]
	v_lshl_add_u64 v[34:35], v[26:27], 0, s[10:11]
	v_lshl_add_u64 v[36:37], v[26:27], 0, s[20:21]
	global_load_ushort v38, v[26:27], off
	global_load_ushort v42, v[34:35], off
	global_load_ushort v46, v[36:37], off
	v_lshl_add_u64 v[28:29], v[22:23], 0, v[18:19]
	v_lshl_add_u64 v[34:35], v[28:29], 0, s[10:11]
	v_lshl_add_u64 v[36:37], v[28:29], 0, s[20:21]
	global_load_ushort v39, v[28:29], off
	global_load_ushort v43, v[34:35], off
	global_load_ushort v47, v[36:37], off
	v_or_b32_e32 v21, s18, v69
	v_mad_i64_i32 v[24:25], s[0:1], v21, s23, v[14:15]
	v_lshl_add_u64 v[24:25], v[24:25], 0, s[16:17]
	v_lshl_add_u64 v[30:31], v[24:25], 0, v[0:1]
	v_lshl_add_u64 v[34:35], v[30:31], 0, s[10:11]
	v_lshl_add_u64 v[36:37], v[30:31], 0, s[20:21]
	global_load_ushort v40, v[30:31], off
	global_load_ushort v44, v[34:35], off
	global_load_ushort v48, v[36:37], off
	v_lshl_add_u64 v[32:33], v[24:25], 0, v[18:19]
	v_lshl_add_u64 v[34:35], v[32:33], 0, s[10:11]
	v_lshl_add_u64 v[36:37], v[32:33], 0, s[20:21]
	global_load_ushort v41, v[32:33], off
	global_load_ushort v45, v[34:35], off
	global_load_ushort v49, v[36:37], off
	s_waitcnt vmcnt(0)
	v_and_b32_e32 v54, v71, v20
	v_lshlrev_b32_e32 v55, 16, v38
	v_lshlrev_b32_e32 v56, 16, v42
	v_lshlrev_b32_e32 v57, 16, v46
	v_cmp_ne_u32_e32 vcc, 0, v54
	s_nop 1
	v_cndmask_b32_e32 v56, 0, v56, vcc
	v_cmp_ne_u32_e32 vcc, s22, v54
	s_nop 1
	v_cndmask_b32_e32 v57, 0, v57, vcc
	v_sub_f32_e32 v56, v56, v55
	v_sub_f32_e32 v57, v57, v55
	v_mul_f32_e32 v56, v56, v50
	v_mul_f32_e32 v57, v57, v51
	v_add_f32_e32 v56, v56, v55
	v_add_f32_e32 v56, v56, v57
	v_add_f32_e64 v57, |v56|, |v56|
	v_mul_f32_e32 v58, 0x3fb8aa3b, v57
	v_rndne_f32_e32 v59, v58
	v_sub_f32_e32 v60, v58, v59
	v_fma_f32 v58, v57, s35, -v58
	v_fmac_f32_e32 v58, 0x32a5705f, v57
	v_add_f32_e32 v58, v60, v58
	v_cvt_i32_f32_e32 v59, v59
	v_exp_f32_e32 v58, v58
	v_cmp_ngt_f32_e32 vcc, s44, v57
	v_ldexp_f32 v58, v58, v59
	s_nop 0
	v_cndmask_b32_e32 v58, 0, v58, vcc
	v_cmp_nlt_f32_e32 vcc, s45, v57
	s_nop 1
	v_cndmask_b32_e32 v57, v73, v58, vcc
	v_add_f32_e32 v57, 1.0, v57
	v_rcp_f32_e32 v57, v57
	s_nop 0
	v_fma_f32 v58, v57, -2.0, 1.0
	v_mul_f32_e32 v57, v56, v56
	v_fmamk_f32 v59, v57, 0xbbbac73d, v72
	v_fmaak_f32 v59, v57, v59, 0xbd5c1c4e
	v_fmaak_f32 v59, v57, v59, 0x3e088382
	v_fmaak_f32 v59, v57, v59, 0xbeaaaa99
	v_mul_f32_e64 v59, |v56|, v59
	v_fma_f32 v59, v57, v59, |v56|
	v_cmp_nlt_f32_e64 vcc, |v56|, s34
	s_nop 1
	v_cndmask_b32_e32 v58, v59, v58, vcc
	v_bfi_b32 v56, s46, v58, v56
	ds_write_b32 v68, v56
	v_and_b32_e32 v54, v71, v20
	v_lshlrev_b32_e32 v55, 16, v39
	v_lshlrev_b32_e32 v56, 16, v43
	v_lshlrev_b32_e32 v57, 16, v47
	v_cmp_ne_u32_e32 vcc, 0, v54
	s_nop 1
	v_cndmask_b32_e32 v56, 0, v56, vcc
	v_cmp_ne_u32_e32 vcc, s22, v54
	s_nop 1
	v_cndmask_b32_e32 v57, 0, v57, vcc
	v_sub_f32_e32 v56, v56, v55
	v_sub_f32_e32 v57, v57, v55
	v_mul_f32_e32 v56, v56, v52
	v_mul_f32_e32 v57, v57, v53
	v_add_f32_e32 v56, v56, v55
	v_add_f32_e32 v56, v56, v57
	ds_write_b32 v68, v56 offset:4096
	v_and_b32_e32 v54, v71, v21
	v_lshlrev_b32_e32 v55, 16, v40
	v_lshlrev_b32_e32 v56, 16, v44
	v_lshlrev_b32_e32 v57, 16, v48
	v_cmp_ne_u32_e32 vcc, 0, v54
	s_nop 1
	v_cndmask_b32_e32 v56, 0, v56, vcc
	v_cmp_ne_u32_e32 vcc, s22, v54
	s_nop 1
	v_cndmask_b32_e32 v57, 0, v57, vcc
	v_sub_f32_e32 v56, v56, v55
	v_sub_f32_e32 v57, v57, v55
	v_mul_f32_e32 v56, v56, v50
	v_mul_f32_e32 v57, v57, v51
	v_add_f32_e32 v56, v56, v55
	v_add_f32_e32 v56, v56, v57
	v_add_f32_e64 v57, |v56|, |v56|
	v_mul_f32_e32 v58, 0x3fb8aa3b, v57
	v_rndne_f32_e32 v59, v58
	v_sub_f32_e32 v60, v58, v59
	v_fma_f32 v58, v57, s35, -v58
	v_fmac_f32_e32 v58, 0x32a5705f, v57
	v_add_f32_e32 v58, v60, v58
	v_cvt_i32_f32_e32 v59, v59
	v_exp_f32_e32 v58, v58
	v_cmp_ngt_f32_e32 vcc, s44, v57
	v_ldexp_f32 v58, v58, v59
	s_nop 0
	v_cndmask_b32_e32 v58, 0, v58, vcc
	v_cmp_nlt_f32_e32 vcc, s45, v57
	s_nop 1
	v_cndmask_b32_e32 v57, v73, v58, vcc
	v_add_f32_e32 v57, 1.0, v57
	v_rcp_f32_e32 v57, v57
	s_nop 0
	v_fma_f32 v58, v57, -2.0, 1.0
	v_mul_f32_e32 v57, v56, v56
	v_fmamk_f32 v59, v57, 0xbbbac73d, v72
	v_fmaak_f32 v59, v57, v59, 0xbd5c1c4e
	v_fmaak_f32 v59, v57, v59, 0x3e088382
	v_fmaak_f32 v59, v57, v59, 0xbeaaaa99
	v_mul_f32_e64 v59, |v56|, v59
	v_fma_f32 v59, v57, v59, |v56|
	v_cmp_nlt_f32_e64 vcc, |v56|, s34
	s_nop 1
	v_cndmask_b32_e32 v58, v59, v58, vcc
	v_bfi_b32 v56, s46, v58, v56
	ds_write_b32 v70, v56
	v_and_b32_e32 v54, v71, v21
	v_lshlrev_b32_e32 v55, 16, v41
	v_lshlrev_b32_e32 v56, 16, v45
	v_lshlrev_b32_e32 v57, 16, v49
	v_cmp_ne_u32_e32 vcc, 0, v54
	s_nop 1
	v_cndmask_b32_e32 v56, 0, v56, vcc
	v_cmp_ne_u32_e32 vcc, s22, v54
	s_nop 1
	v_cndmask_b32_e32 v57, 0, v57, vcc
	v_sub_f32_e32 v56, v56, v55
	v_sub_f32_e32 v57, v57, v55
	v_mul_f32_e32 v56, v56, v52
	v_mul_f32_e32 v57, v57, v53
	v_add_f32_e32 v56, v56, v55
	v_add_f32_e32 v56, v56, v57
	ds_write_b32 v70, v56 offset:4096
	s_waitcnt lgkmcnt(0)
	s_barrier
	v_and_b32_e32 v112, 63, v164
	v_lshrrev_b32_e32 v113, 6, v164
	v_lshlrev_b32_e32 v107, 2, v112
	v_lshrrev_b32_e32 v114, 4, v112
	v_and_b32_e32 v115, 15, v112
	v_lshlrev_b32_e32 v111, 11, v114
	v_lshl_add_u32 v111, v113, 8, v111
	v_lshl_add_u32 v111, v115, 4, v111
	v_mul_u32_u24_e32 v110, 0x3000, v113
	v_add_u32_e32 v110, 0x2000, v110
	v_lshl_add_u32 v109, v114, 10, v110
	v_lshl_add_u32 v109, v115, 4, v109
	v_lshl_add_u32 v110, v112, 2, v110
	v_readlane_b32 s50, v255, 27
	v_readlane_b32 s51, v255, 28
	v_readlane_b32 s54, v255, 31
	v_readlane_b32 s55, v255, 32
	s_add_u32 s52, s50, 0x20000
	s_addc_u32 s53, s51, 0
	v_mov_b32_e32 v108, v111
	global_load_dwordx4 v[92:95], v108, s[50:51]
	v_add_u32_e32 v108, 0x2000, v108
	ds_read_b32 v104, v107 offset:0
	global_load_dwordx4 v[96:99], v108, s[50:51]
	v_add_u32_e32 v108, 0x2000, v108
	ds_read_b32 v105, v107 offset:256
	global_load_dwordx4 v[100:103], v108, s[50:51]
	v_add_u32_e32 v108, 0x2000, v108
	ds_read_b32 v106, v107 offset:512
	global_load_dwordx4 v[20:23], v108, s[50:51]
	v_add_u32_e32 v108, 0x2000, v108
	ds_read_b32 v28, v107 offset:768
	global_load_dwordx4 v[24:27], v108, s[50:51]
	v_add_u32_e32 v108, 0x2000, v108
	ds_read_b32 v29, v107 offset:1024
	global_load_dwordx4 v[32:35], v108, s[50:51]
	v_add_u32_e32 v108, 0x2000, v108
	ds_read_b32 v30, v107 offset:1280
	global_load_dwordx4 v[36:39], v108, s[50:51]
	v_add_u32_e32 v108, 0x2000, v108
	ds_read_b32 v31, v107 offset:1536
	s_waitcnt vmcnt(6) lgkmcnt(6)
	v_mfma_f32_16x16x4_f32 v[76:79], v104, v92, 0
	v_mfma_f32_16x16x4_f32 v[80:83], v104, v93, 0
	v_mfma_f32_16x16x4_f32 v[84:87], v104, v94, 0
	v_mfma_f32_16x16x4_f32 v[88:91], v104, v95, 0
	global_load_dwordx4 v[92:95], v108, s[50:51]
	v_add_u32_e32 v108, 0x2000, v108
	ds_read_b32 v104, v107 offset:1792
	s_waitcnt vmcnt(6) lgkmcnt(6)
	v_mfma_f32_16x16x4_f32 v[76:79], v105, v96, v[76:79]
	v_mfma_f32_16x16x4_f32 v[80:83], v105, v97, v[80:83]
	v_mfma_f32_16x16x4_f32 v[84:87], v105, v98, v[84:87]
	v_mfma_f32_16x16x4_f32 v[88:91], v105, v99, v[88:91]
	global_load_dwordx4 v[96:99], v108, s[50:51]
	v_add_u32_e32 v108, 0x2000, v108
	ds_read_b32 v105, v107 offset:2048
	s_waitcnt vmcnt(6) lgkmcnt(6)
	v_mfma_f32_16x16x4_f32 v[76:79], v106, v100, v[76:79]
	v_mfma_f32_16x16x4_f32 v[80:83], v106, v101, v[80:83]
	v_mfma_f32_16x16x4_f32 v[84:87], v106, v102, v[84:87]
	v_mfma_f32_16x16x4_f32 v[88:91], v106, v103, v[88:91]
	global_load_dwordx4 v[100:103], v108, s[50:51]
	v_add_u32_e32 v108, 0x2000, v108
	ds_read_b32 v106, v107 offset:2304
	s_waitcnt vmcnt(6) lgkmcnt(6)
	v_mfma_f32_16x16x4_f32 v[76:79], v28, v20, v[76:79]
	v_mfma_f32_16x16x4_f32 v[80:83], v28, v21, v[80:83]
	v_mfma_f32_16x16x4_f32 v[84:87], v28, v22, v[84:87]
	v_mfma_f32_16x16x4_f32 v[88:91], v28, v23, v[88:91]
	global_load_dwordx4 v[20:23], v108, s[50:51]
	v_add_u32_e32 v108, 0x2000, v108
	ds_read_b32 v28, v107 offset:2560
	s_waitcnt vmcnt(6) lgkmcnt(6)
	v_mfma_f32_16x16x4_f32 v[76:79], v29, v24, v[76:79]
	v_mfma_f32_16x16x4_f32 v[80:83], v29, v25, v[80:83]
	v_mfma_f32_16x16x4_f32 v[84:87], v29, v26, v[84:87]
	v_mfma_f32_16x16x4_f32 v[88:91], v29, v27, v[88:91]
	global_load_dwordx4 v[24:27], v108, s[50:51]
	v_add_u32_e32 v108, 0x2000, v108
	ds_read_b32 v29, v107 offset:2816
	s_waitcnt vmcnt(6) lgkmcnt(6)
	v_mfma_f32_16x16x4_f32 v[76:79], v30, v32, v[76:79]
	v_mfma_f32_16x16x4_f32 v[80:83], v30, v33, v[80:83]
	v_mfma_f32_16x16x4_f32 v[84:87], v30, v34, v[84:87]
	v_mfma_f32_16x16x4_f32 v[88:91], v30, v35, v[88:91]
	global_load_dwordx4 v[32:35], v108, s[50:51]
	v_add_u32_e32 v108, 0x2000, v108
	ds_read_b32 v30, v107 offset:3072
	s_waitcnt vmcnt(6) lgkmcnt(6)
	v_mfma_f32_16x16x4_f32 v[76:79], v31, v36, v[76:79]
	v_mfma_f32_16x16x4_f32 v[80:83], v31, v37, v[80:83]
	v_mfma_f32_16x16x4_f32 v[84:87], v31, v38, v[84:87]
	v_mfma_f32_16x16x4_f32 v[88:91], v31, v39, v[88:91]
	global_load_dwordx4 v[36:39], v108, s[50:51]
	v_add_u32_e32 v108, 0x2000, v108
	ds_read_b32 v31, v107 offset:3328
	s_waitcnt vmcnt(6) lgkmcnt(6)
	v_mfma_f32_16x16x4_f32 v[76:79], v104, v92, v[76:79]
	v_mfma_f32_16x16x4_f32 v[80:83], v104, v93, v[80:83]
	v_mfma_f32_16x16x4_f32 v[84:87], v104, v94, v[84:87]
	v_mfma_f32_16x16x4_f32 v[88:91], v104, v95, v[88:91]
	global_load_dwordx4 v[92:95], v108, s[50:51]
	v_add_u32_e32 v108, 0x2000, v108
	ds_read_b32 v104, v107 offset:3584
	s_waitcnt vmcnt(6) lgkmcnt(6)
	v_mfma_f32_16x16x4_f32 v[76:79], v105, v96, v[76:79]
	v_mfma_f32_16x16x4_f32 v[80:83], v105, v97, v[80:83]
	v_mfma_f32_16x16x4_f32 v[84:87], v105, v98, v[84:87]
	v_mfma_f32_16x16x4_f32 v[88:91], v105, v99, v[88:91]
	global_load_dwordx4 v[96:99], v108, s[50:51]
	v_add_u32_e32 v108, 0x2000, v108
	ds_read_b32 v105, v107 offset:3840
	s_waitcnt vmcnt(6) lgkmcnt(6)
	v_mfma_f32_16x16x4_f32 v[76:79], v106, v100, v[76:79]
	v_mfma_f32_16x16x4_f32 v[80:83], v106, v101, v[80:83]
	v_mfma_f32_16x16x4_f32 v[84:87], v106, v102, v[84:87]
	v_mfma_f32_16x16x4_f32 v[88:91], v106, v103, v[88:91]
	v_mov_b32_e32 v108, v111
	global_load_dwordx4 v[100:103], v108, s[52:53]
	v_add_u32_e32 v108, 0x2000, v108
	ds_read_b32 v106, v107 offset:0
	s_waitcnt vmcnt(6) lgkmcnt(6)
	v_mfma_f32_16x16x4_f32 v[76:79], v28, v20, v[76:79]
	v_mfma_f32_16x16x4_f32 v[80:83], v28, v21, v[80:83]
	v_mfma_f32_16x16x4_f32 v[84:87], v28, v22, v[84:87]
	v_mfma_f32_16x16x4_f32 v[88:91], v28, v23, v[88:91]
	global_load_dwordx4 v[20:23], v108, s[52:53]
	v_add_u32_e32 v108, 0x2000, v108
	ds_read_b32 v28, v107 offset:256
	s_waitcnt vmcnt(6) lgkmcnt(6)
	v_mfma_f32_16x16x4_f32 v[76:79], v29, v24, v[76:79]
	v_mfma_f32_16x16x4_f32 v[80:83], v29, v25, v[80:83]
	v_mfma_f32_16x16x4_f32 v[84:87], v29, v26, v[84:87]
	v_mfma_f32_16x16x4_f32 v[88:91], v29, v27, v[88:91]
	global_load_dwordx4 v[24:27], v108, s[52:53]
	v_add_u32_e32 v108, 0x2000, v108
	ds_read_b32 v29, v107 offset:512
	s_waitcnt vmcnt(6) lgkmcnt(6)
	v_mfma_f32_16x16x4_f32 v[76:79], v30, v32, v[76:79]
	v_mfma_f32_16x16x4_f32 v[80:83], v30, v33, v[80:83]
	v_mfma_f32_16x16x4_f32 v[84:87], v30, v34, v[84:87]
	v_mfma_f32_16x16x4_f32 v[88:91], v30, v35, v[88:91]
	global_load_dwordx4 v[32:35], v108, s[52:53]
	v_add_u32_e32 v108, 0x2000, v108
	ds_read_b32 v30, v107 offset:768
	s_waitcnt vmcnt(6) lgkmcnt(6)
	v_mfma_f32_16x16x4_f32 v[76:79], v31, v36, v[76:79]
	v_mfma_f32_16x16x4_f32 v[80:83], v31, v37, v[80:83]
	v_mfma_f32_16x16x4_f32 v[84:87], v31, v38, v[84:87]
	v_mfma_f32_16x16x4_f32 v[88:91], v31, v39, v[88:91]
	global_load_dwordx4 v[36:39], v108, s[52:53]
	v_add_u32_e32 v108, 0x2000, v108
	ds_read_b32 v31, v107 offset:1024
	s_waitcnt vmcnt(6) lgkmcnt(6)
	v_mfma_f32_16x16x4_f32 v[76:79], v104, v92, v[76:79]
	v_mfma_f32_16x16x4_f32 v[80:83], v104, v93, v[80:83]
	v_mfma_f32_16x16x4_f32 v[84:87], v104, v94, v[84:87]
	v_mfma_f32_16x16x4_f32 v[88:91], v104, v95, v[88:91]
	global_load_dwordx4 v[92:95], v108, s[52:53]
	v_add_u32_e32 v108, 0x2000, v108
	ds_read_b32 v104, v107 offset:1280
	s_waitcnt vmcnt(6) lgkmcnt(6)
	v_mfma_f32_16x16x4_f32 v[76:79], v105, v96, v[76:79]
	v_mfma_f32_16x16x4_f32 v[80:83], v105, v97, v[80:83]
	v_mfma_f32_16x16x4_f32 v[84:87], v105, v98, v[84:87]
	v_mfma_f32_16x16x4_f32 v[88:91], v105, v99, v[88:91]
	s_nop 7
	ds_write_b32 v109, v76 offset:0
	ds_write_b32 v109, v77 offset:256
	ds_write_b32 v109, v78 offset:512
	ds_write_b32 v109, v79 offset:768
	ds_write_b32 v109, v80 offset:4
	ds_write_b32 v109, v81 offset:260
	ds_write_b32 v109, v82 offset:516
	ds_write_b32 v109, v83 offset:772
	ds_write_b32 v109, v84 offset:8
	ds_write_b32 v109, v85 offset:264
	ds_write_b32 v109, v86 offset:520
	ds_write_b32 v109, v87 offset:776
	s_nop 15
	s_nop 3
	ds_write_b32 v109, v88 offset:12
	ds_write_b32 v109, v89 offset:268
	ds_write_b32 v109, v90 offset:524
	ds_write_b32 v109, v91 offset:780
	s_waitcnt lgkmcnt(0)
	global_load_dwordx4 v[96:99], v108, s[52:53]
	v_add_u32_e32 v108, 0x2000, v108
	ds_read_b32 v105, v107 offset:1536
	s_waitcnt vmcnt(6) lgkmcnt(6)
	v_mfma_f32_16x16x4_f32 v[76:79], v106, v100, 0
	v_mfma_f32_16x16x4_f32 v[80:83], v106, v101, 0
	v_mfma_f32_16x16x4_f32 v[84:87], v106, v102, 0
	v_mfma_f32_16x16x4_f32 v[88:91], v106, v103, 0
	global_load_dwordx4 v[100:103], v108, s[52:53]
	v_add_u32_e32 v108, 0x2000, v108
	ds_read_b32 v106, v107 offset:1792
	s_waitcnt vmcnt(6) lgkmcnt(6)
	v_mfma_f32_16x16x4_f32 v[76:79], v28, v20, v[76:79]
	v_mfma_f32_16x16x4_f32 v[80:83], v28, v21, v[80:83]
	v_mfma_f32_16x16x4_f32 v[84:87], v28, v22, v[84:87]
	v_mfma_f32_16x16x4_f32 v[88:91], v28, v23, v[88:91]
	global_load_dwordx4 v[20:23], v108, s[52:53]
	v_add_u32_e32 v108, 0x2000, v108
	ds_read_b32 v28, v107 offset:2048
	s_waitcnt vmcnt(6) lgkmcnt(6)
	v_mfma_f32_16x16x4_f32 v[76:79], v29, v24, v[76:79]
	v_mfma_f32_16x16x4_f32 v[80:83], v29, v25, v[80:83]
	v_mfma_f32_16x16x4_f32 v[84:87], v29, v26, v[84:87]
	v_mfma_f32_16x16x4_f32 v[88:91], v29, v27, v[88:91]
	global_load_dwordx4 v[24:27], v108, s[52:53]
	v_add_u32_e32 v108, 0x2000, v108
	ds_read_b32 v29, v107 offset:2304
	s_waitcnt vmcnt(6) lgkmcnt(6)
	v_mfma_f32_16x16x4_f32 v[76:79], v30, v32, v[76:79]
	v_mfma_f32_16x16x4_f32 v[80:83], v30, v33, v[80:83]
	v_mfma_f32_16x16x4_f32 v[84:87], v30, v34, v[84:87]
	v_mfma_f32_16x16x4_f32 v[88:91], v30, v35, v[88:91]
	global_load_dwordx4 v[32:35], v108, s[52:53]
	v_add_u32_e32 v108, 0x2000, v108
	ds_read_b32 v30, v107 offset:2560
	s_waitcnt vmcnt(6) lgkmcnt(6)
	v_mfma_f32_16x16x4_f32 v[76:79], v31, v36, v[76:79]
	v_mfma_f32_16x16x4_f32 v[80:83], v31, v37, v[80:83]
	v_mfma_f32_16x16x4_f32 v[84:87], v31, v38, v[84:87]
	v_mfma_f32_16x16x4_f32 v[88:91], v31, v39, v[88:91]
	global_load_dwordx4 v[36:39], v108, s[52:53]
	v_add_u32_e32 v108, 0x2000, v108
	ds_read_b32 v31, v107 offset:2816
	s_waitcnt vmcnt(6) lgkmcnt(6)
	v_mfma_f32_16x16x4_f32 v[76:79], v104, v92, v[76:79]
	v_mfma_f32_16x16x4_f32 v[80:83], v104, v93, v[80:83]
	v_mfma_f32_16x16x4_f32 v[84:87], v104, v94, v[84:87]
	v_mfma_f32_16x16x4_f32 v[88:91], v104, v95, v[88:91]
	global_load_dwordx4 v[92:95], v108, s[52:53]
	v_add_u32_e32 v108, 0x2000, v108
	ds_read_b32 v104, v107 offset:3072
	s_waitcnt vmcnt(6) lgkmcnt(6)
	v_mfma_f32_16x16x4_f32 v[76:79], v105, v96, v[76:79]
	v_mfma_f32_16x16x4_f32 v[80:83], v105, v97, v[80:83]
	v_mfma_f32_16x16x4_f32 v[84:87], v105, v98, v[84:87]
	v_mfma_f32_16x16x4_f32 v[88:91], v105, v99, v[88:91]
	global_load_dwordx4 v[96:99], v108, s[52:53]
	v_add_u32_e32 v108, 0x2000, v108
	ds_read_b32 v105, v107 offset:3328
	s_waitcnt vmcnt(6) lgkmcnt(6)
	v_mfma_f32_16x16x4_f32 v[76:79], v106, v100, v[76:79]
	v_mfma_f32_16x16x4_f32 v[80:83], v106, v101, v[80:83]
	v_mfma_f32_16x16x4_f32 v[84:87], v106, v102, v[84:87]
	v_mfma_f32_16x16x4_f32 v[88:91], v106, v103, v[88:91]
	global_load_dwordx4 v[100:103], v108, s[52:53]
	v_add_u32_e32 v108, 0x2000, v108
	ds_read_b32 v106, v107 offset:3584
	s_waitcnt vmcnt(6) lgkmcnt(6)
	v_mfma_f32_16x16x4_f32 v[76:79], v28, v20, v[76:79]
	v_mfma_f32_16x16x4_f32 v[80:83], v28, v21, v[80:83]
	v_mfma_f32_16x16x4_f32 v[84:87], v28, v22, v[84:87]
	v_mfma_f32_16x16x4_f32 v[88:91], v28, v23, v[88:91]
	global_load_dwordx4 v[20:23], v108, s[52:53]
	v_add_u32_e32 v108, 0x2000, v108
	ds_read_b32 v28, v107 offset:3840
	s_waitcnt vmcnt(6) lgkmcnt(6)
	v_mfma_f32_16x16x4_f32 v[76:79], v29, v24, v[76:79]
	v_mfma_f32_16x16x4_f32 v[80:83], v29, v25, v[80:83]
	v_mfma_f32_16x16x4_f32 v[84:87], v29, v26, v[84:87]
	v_mfma_f32_16x16x4_f32 v[88:91], v29, v27, v[88:91]
	v_mov_b32_e32 v108, v111
	global_load_dwordx4 v[24:27], v108, s[54:55]
	v_add_u32_e32 v108, 0x2000, v108
	ds_read_b32 v29, v107 offset:4096
	s_waitcnt vmcnt(6) lgkmcnt(6)
	v_mfma_f32_16x16x4_f32 v[76:79], v30, v32, v[76:79]
	v_mfma_f32_16x16x4_f32 v[80:83], v30, v33, v[80:83]
	v_mfma_f32_16x16x4_f32 v[84:87], v30, v34, v[84:87]
	v_mfma_f32_16x16x4_f32 v[88:91], v30, v35, v[88:91]
	global_load_dwordx4 v[32:35], v108, s[54:55]
	v_add_u32_e32 v108, 0x2000, v108
	ds_read_b32 v30, v107 offset:4352
	s_waitcnt vmcnt(6) lgkmcnt(6)
	v_mfma_f32_16x16x4_f32 v[76:79], v31, v36, v[76:79]
	v_mfma_f32_16x16x4_f32 v[80:83], v31, v37, v[80:83]
	v_mfma_f32_16x16x4_f32 v[84:87], v31, v38, v[84:87]
	v_mfma_f32_16x16x4_f32 v[88:91], v31, v39, v[88:91]
	global_load_dwordx4 v[36:39], v108, s[54:55]
	v_add_u32_e32 v108, 0x2000, v108
	ds_read_b32 v31, v107 offset:4608
	s_waitcnt vmcnt(6) lgkmcnt(6)
	v_mfma_f32_16x16x4_f32 v[76:79], v104, v92, v[76:79]
	v_mfma_f32_16x16x4_f32 v[80:83], v104, v93, v[80:83]
	v_mfma_f32_16x16x4_f32 v[84:87], v104, v94, v[84:87]
	v_mfma_f32_16x16x4_f32 v[88:91], v104, v95, v[88:91]
	global_load_dwordx4 v[92:95], v108, s[54:55]
	v_add_u32_e32 v108, 0x2000, v108
	ds_read_b32 v104, v107 offset:4864
	s_waitcnt vmcnt(6) lgkmcnt(6)
	v_mfma_f32_16x16x4_f32 v[76:79], v105, v96, v[76:79]
	v_mfma_f32_16x16x4_f32 v[80:83], v105, v97, v[80:83]
	v_mfma_f32_16x16x4_f32 v[84:87], v105, v98, v[84:87]
	v_mfma_f32_16x16x4_f32 v[88:91], v105, v99, v[88:91]
	global_load_dwordx4 v[96:99], v108, s[54:55]
	v_add_u32_e32 v108, 0x2000, v108
	ds_read_b32 v105, v107 offset:5120
	s_waitcnt vmcnt(6) lgkmcnt(6)
	v_mfma_f32_16x16x4_f32 v[76:79], v106, v100, v[76:79]
	v_mfma_f32_16x16x4_f32 v[80:83], v106, v101, v[80:83]
	v_mfma_f32_16x16x4_f32 v[84:87], v106, v102, v[84:87]
	v_mfma_f32_16x16x4_f32 v[88:91], v106, v103, v[88:91]
	global_load_dwordx4 v[100:103], v108, s[54:55]
	v_add_u32_e32 v108, 0x2000, v108
	ds_read_b32 v106, v107 offset:5376
	s_waitcnt vmcnt(6) lgkmcnt(6)
	v_mfma_f32_16x16x4_f32 v[76:79], v28, v20, v[76:79]
	v_mfma_f32_16x16x4_f32 v[80:83], v28, v21, v[80:83]
	v_mfma_f32_16x16x4_f32 v[84:87], v28, v22, v[84:87]
	v_mfma_f32_16x16x4_f32 v[88:91], v28, v23, v[88:91]
	s_nop 7
	ds_write_b32 v109, v76 offset:4096
	ds_write_b32 v109, v77 offset:4352
	ds_write_b32 v109, v78 offset:4608
	ds_write_b32 v109, v79 offset:4864
	ds_write_b32 v109, v80 offset:4100
	ds_write_b32 v109, v81 offset:4356
	ds_write_b32 v109, v82 offset:4612
	ds_write_b32 v109, v83 offset:4868
	ds_write_b32 v109, v84 offset:4104
	ds_write_b32 v109, v85 offset:4360
	ds_write_b32 v109, v86 offset:4616
	ds_write_b32 v109, v87 offset:4872
	s_nop 15
	s_nop 3
	ds_write_b32 v109, v88 offset:4108
	ds_write_b32 v109, v89 offset:4364
	ds_write_b32 v109, v90 offset:4620
	ds_write_b32 v109, v91 offset:4876
	s_waitcnt lgkmcnt(0)
	global_load_dwordx4 v[20:23], v108, s[54:55]
	v_add_u32_e32 v108, 0x2000, v108
	ds_read_b32 v28, v107 offset:5632
	s_waitcnt vmcnt(6) lgkmcnt(6)
	v_mfma_f32_16x16x4_f32 v[76:79], v29, v24, 0
	v_mfma_f32_16x16x4_f32 v[80:83], v29, v25, 0
	v_mfma_f32_16x16x4_f32 v[84:87], v29, v26, 0
	v_mfma_f32_16x16x4_f32 v[88:91], v29, v27, 0
	global_load_dwordx4 v[24:27], v108, s[54:55]
	v_add_u32_e32 v108, 0x2000, v108
	ds_read_b32 v29, v107 offset:5888
	s_waitcnt vmcnt(6) lgkmcnt(6)
	v_mfma_f32_16x16x4_f32 v[76:79], v30, v32, v[76:79]
	v_mfma_f32_16x16x4_f32 v[80:83], v30, v33, v[80:83]
	v_mfma_f32_16x16x4_f32 v[84:87], v30, v34, v[84:87]
	v_mfma_f32_16x16x4_f32 v[88:91], v30, v35, v[88:91]
	global_load_dwordx4 v[32:35], v108, s[54:55]
	v_add_u32_e32 v108, 0x2000, v108
	ds_read_b32 v30, v107 offset:6144
	s_waitcnt vmcnt(6) lgkmcnt(6)
	v_mfma_f32_16x16x4_f32 v[76:79], v31, v36, v[76:79]
	v_mfma_f32_16x16x4_f32 v[80:83], v31, v37, v[80:83]
	v_mfma_f32_16x16x4_f32 v[84:87], v31, v38, v[84:87]
	v_mfma_f32_16x16x4_f32 v[88:91], v31, v39, v[88:91]
	global_load_dwordx4 v[36:39], v108, s[54:55]
	v_add_u32_e32 v108, 0x2000, v108
	ds_read_b32 v31, v107 offset:6400
	s_waitcnt vmcnt(6) lgkmcnt(6)
	v_mfma_f32_16x16x4_f32 v[76:79], v104, v92, v[76:79]
	v_mfma_f32_16x16x4_f32 v[80:83], v104, v93, v[80:83]
	v_mfma_f32_16x16x4_f32 v[84:87], v104, v94, v[84:87]
	v_mfma_f32_16x16x4_f32 v[88:91], v104, v95, v[88:91]
	global_load_dwordx4 v[92:95], v108, s[54:55]
	v_add_u32_e32 v108, 0x2000, v108
	ds_read_b32 v104, v107 offset:6656
	s_waitcnt vmcnt(6) lgkmcnt(6)
	v_mfma_f32_16x16x4_f32 v[76:79], v105, v96, v[76:79]
	v_mfma_f32_16x16x4_f32 v[80:83], v105, v97, v[80:83]
	v_mfma_f32_16x16x4_f32 v[84:87], v105, v98, v[84:87]
	v_mfma_f32_16x16x4_f32 v[88:91], v105, v99, v[88:91]
	global_load_dwordx4 v[96:99], v108, s[54:55]
	v_add_u32_e32 v108, 0x2000, v108
	ds_read_b32 v105, v107 offset:6912
	s_waitcnt vmcnt(6) lgkmcnt(6)
	v_mfma_f32_16x16x4_f32 v[76:79], v106, v100, v[76:79]
	v_mfma_f32_16x16x4_f32 v[80:83], v106, v101, v[80:83]
	v_mfma_f32_16x16x4_f32 v[84:87], v106, v102, v[84:87]
	v_mfma_f32_16x16x4_f32 v[88:91], v106, v103, v[88:91]
	global_load_dwordx4 v[100:103], v108, s[54:55]
	v_add_u32_e32 v108, 0x2000, v108
	ds_read_b32 v106, v107 offset:7168
	s_waitcnt vmcnt(6) lgkmcnt(6)
	v_mfma_f32_16x16x4_f32 v[76:79], v28, v20, v[76:79]
	v_mfma_f32_16x16x4_f32 v[80:83], v28, v21, v[80:83]
	v_mfma_f32_16x16x4_f32 v[84:87], v28, v22, v[84:87]
	v_mfma_f32_16x16x4_f32 v[88:91], v28, v23, v[88:91]
	global_load_dwordx4 v[20:23], v108, s[54:55]
	v_add_u32_e32 v108, 0x2000, v108
	ds_read_b32 v28, v107 offset:7424
	s_waitcnt vmcnt(6) lgkmcnt(6)
	v_mfma_f32_16x16x4_f32 v[76:79], v29, v24, v[76:79]
	v_mfma_f32_16x16x4_f32 v[80:83], v29, v25, v[80:83]
	v_mfma_f32_16x16x4_f32 v[84:87], v29, v26, v[84:87]
	v_mfma_f32_16x16x4_f32 v[88:91], v29, v27, v[88:91]
	global_load_dwordx4 v[24:27], v108, s[54:55]
	v_add_u32_e32 v108, 0x2000, v108
	ds_read_b32 v29, v107 offset:7680
	s_waitcnt vmcnt(6) lgkmcnt(6)
	v_mfma_f32_16x16x4_f32 v[76:79], v30, v32, v[76:79]
	v_mfma_f32_16x16x4_f32 v[80:83], v30, v33, v[80:83]
	v_mfma_f32_16x16x4_f32 v[84:87], v30, v34, v[84:87]
	v_mfma_f32_16x16x4_f32 v[88:91], v30, v35, v[88:91]
	global_load_dwordx4 v[32:35], v108, s[54:55]
	v_add_u32_e32 v108, 0x2000, v108
	ds_read_b32 v30, v107 offset:7936
	s_waitcnt vmcnt(6) lgkmcnt(6)
	v_mfma_f32_16x16x4_f32 v[76:79], v31, v36, v[76:79]
	v_mfma_f32_16x16x4_f32 v[80:83], v31, v37, v[80:83]
	v_mfma_f32_16x16x4_f32 v[84:87], v31, v38, v[84:87]
	v_mfma_f32_16x16x4_f32 v[88:91], v31, v39, v[88:91]
	s_waitcnt vmcnt(5) lgkmcnt(5)
	v_mfma_f32_16x16x4_f32 v[76:79], v104, v92, v[76:79]
	v_mfma_f32_16x16x4_f32 v[80:83], v104, v93, v[80:83]
	v_mfma_f32_16x16x4_f32 v[84:87], v104, v94, v[84:87]
	v_mfma_f32_16x16x4_f32 v[88:91], v104, v95, v[88:91]
	s_waitcnt vmcnt(4) lgkmcnt(4)
	v_mfma_f32_16x16x4_f32 v[76:79], v105, v96, v[76:79]
	v_mfma_f32_16x16x4_f32 v[80:83], v105, v97, v[80:83]
	v_mfma_f32_16x16x4_f32 v[84:87], v105, v98, v[84:87]
	v_mfma_f32_16x16x4_f32 v[88:91], v105, v99, v[88:91]
	s_waitcnt vmcnt(3) lgkmcnt(3)
	v_mfma_f32_16x16x4_f32 v[76:79], v106, v100, v[76:79]
	v_mfma_f32_16x16x4_f32 v[80:83], v106, v101, v[80:83]
	v_mfma_f32_16x16x4_f32 v[84:87], v106, v102, v[84:87]
	v_mfma_f32_16x16x4_f32 v[88:91], v106, v103, v[88:91]
	s_waitcnt vmcnt(2) lgkmcnt(2)
	v_mfma_f32_16x16x4_f32 v[76:79], v28, v20, v[76:79]
	v_mfma_f32_16x16x4_f32 v[80:83], v28, v21, v[80:83]
	v_mfma_f32_16x16x4_f32 v[84:87], v28, v22, v[84:87]
	v_mfma_f32_16x16x4_f32 v[88:91], v28, v23, v[88:91]
	s_waitcnt vmcnt(1) lgkmcnt(1)
	v_mfma_f32_16x16x4_f32 v[76:79], v29, v24, v[76:79]
	v_mfma_f32_16x16x4_f32 v[80:83], v29, v25, v[80:83]
	v_mfma_f32_16x16x4_f32 v[84:87], v29, v26, v[84:87]
	v_mfma_f32_16x16x4_f32 v[88:91], v29, v27, v[88:91]
	s_waitcnt vmcnt(0) lgkmcnt(0)
	v_mfma_f32_16x16x4_f32 v[76:79], v30, v32, v[76:79]
	v_mfma_f32_16x16x4_f32 v[80:83], v30, v33, v[80:83]
	v_mfma_f32_16x16x4_f32 v[84:87], v30, v34, v[84:87]
	v_mfma_f32_16x16x4_f32 v[88:91], v30, v35, v[88:91]
	s_nop 7
	ds_write_b32 v109, v76 offset:8192
	ds_write_b32 v109, v77 offset:8448
	ds_write_b32 v109, v78 offset:8704
	ds_write_b32 v109, v79 offset:8960
	ds_write_b32 v109, v80 offset:8196
	ds_write_b32 v109, v81 offset:8452
	ds_write_b32 v109, v82 offset:8708
	ds_write_b32 v109, v83 offset:8964
	ds_write_b32 v109, v84 offset:8200
	ds_write_b32 v109, v85 offset:8456
	ds_write_b32 v109, v86 offset:8712
	ds_write_b32 v109, v87 offset:8968
	s_nop 15
	s_nop 3
	ds_write_b32 v109, v88 offset:8204
	ds_write_b32 v109, v89 offset:8460
	ds_write_b32 v109, v90 offset:8716
	ds_write_b32 v109, v91 offset:8972
	s_waitcnt lgkmcnt(0)
	ds_read2st64_b32 v[62:63], v110 offset0:0 offset1:1
	ds_read2st64_b32 v[56:57], v110 offset0:2 offset1:3
	ds_read2st64_b32 v[50:51], v110 offset0:4 offset1:5
	ds_read2st64_b32 v[44:45], v110 offset0:6 offset1:7
	ds_read2st64_b32 v[38:39], v110 offset0:8 offset1:9
	ds_read2st64_b32 v[32:33], v110 offset0:10 offset1:11
	ds_read2st64_b32 v[26:27], v110 offset0:12 offset1:13
	ds_read2st64_b32 v[20:21], v110 offset0:14 offset1:15
	ds_read2st64_b32 v[64:65], v110 offset0:16 offset1:17
	ds_read2st64_b32 v[58:59], v110 offset0:18 offset1:19
	ds_read2st64_b32 v[52:53], v110 offset0:20 offset1:21
	ds_read2st64_b32 v[46:47], v110 offset0:22 offset1:23
	s_waitcnt lgkmcnt(0)
	ds_read2st64_b32 v[40:41], v110 offset0:24 offset1:25
	ds_read2st64_b32 v[34:35], v110 offset0:26 offset1:27
	ds_read2st64_b32 v[28:29], v110 offset0:28 offset1:29
	ds_read2st64_b32 v[22:23], v110 offset0:30 offset1:31
	ds_read2st64_b32 v[66:67], v110 offset0:32 offset1:33
	ds_read2st64_b32 v[60:61], v110 offset0:34 offset1:35
	ds_read2st64_b32 v[54:55], v110 offset0:36 offset1:37
	ds_read2st64_b32 v[48:49], v110 offset0:38 offset1:39
	ds_read2st64_b32 v[42:43], v110 offset0:40 offset1:41
	ds_read2st64_b32 v[36:37], v110 offset0:42 offset1:43
	ds_read2st64_b32 v[30:31], v110 offset0:44 offset1:45
	ds_read2st64_b32 v[24:25], v110 offset0:46 offset1:47
	s_waitcnt lgkmcnt(0)
	s_waitcnt lgkmcnt(0)
	s_ashr_i32 s19, s18, 31
	s_lshl_b64 s[0:1], s[18:19], 10
	v_lshlrev_b32_e32 v78, 1, v164
	v_or_b32_e32 v74, s0, v78
	v_mov_b32_e32 v75, s1
	s_or_b32 s0, s18, 1
	v_cvt_pk_bf16_f32 v17, v62, v1
	v_lshl_add_u64 v[76:77], s[12:13], 0, v[74:75]
	s_ashr_i32 s1, s0, 31
	global_store_short v[76:77], v17, off
	v_cvt_pk_bf16_f32 v17, v64, v1
	v_lshl_add_u64 v[76:77], s[14:15], 0, v[74:75]
	v_lshl_add_u64 v[74:75], s[92:93], 0, v[74:75]
	s_lshl_b64 s[0:1], s[0:1], 9
	global_store_short v[76:77], v17, off
	v_cvt_pk_bf16_f32 v17, v66, v1
	global_store_short v[74:75], v17, off
	v_lshl_add_u64 v[74:75], s[0:1], 0, v[164:165]
	v_cvt_pk_bf16_f32 v17, v63, v1
	v_lshlrev_b64 v[62:63], 1, v[74:75]
	s_or_b32 s0, s18, 2
	v_lshl_add_u64 v[74:75], s[12:13], 0, v[62:63]
	s_ashr_i32 s1, s0, 31
	global_store_short v[74:75], v17, off
	v_cvt_pk_bf16_f32 v17, v65, v1
	v_lshl_add_u64 v[64:65], s[14:15], 0, v[62:63]
	v_lshl_add_u64 v[62:63], s[92:93], 0, v[62:63]
	s_lshl_b64 s[0:1], s[0:1], 10
	global_store_short v[64:65], v17, off
	v_cvt_pk_bf16_f32 v17, v67, v1
	global_store_short v[62:63], v17, off
	v_or_b32_e32 v62, s0, v78
	v_mov_b32_e32 v63, s1
	s_or_b32 s0, s18, 3
	v_cvt_pk_bf16_f32 v17, v56, v1
	v_lshl_add_u64 v[64:65], s[12:13], 0, v[62:63]
	s_ashr_i32 s1, s0, 31
	global_store_short v[64:65], v17, off
	v_cvt_pk_bf16_f32 v17, v58, v1
	v_lshl_add_u64 v[64:65], s[14:15], 0, v[62:63]
	v_lshl_add_u64 v[62:63], s[92:93], 0, v[62:63]
	s_lshl_b64 s[0:1], s[0:1], 9
	global_store_short v[64:65], v17, off
	v_cvt_pk_bf16_f32 v17, v60, v1
	global_store_short v[62:63], v17, off
	v_lshl_add_u64 v[62:63], s[0:1], 0, v[164:165]
	v_cvt_pk_bf16_f32 v17, v57, v1
	v_lshlrev_b64 v[56:57], 1, v[62:63]
	s_or_b32 s0, s18, 4
	v_lshl_add_u64 v[62:63], s[12:13], 0, v[56:57]
	s_ashr_i32 s1, s0, 31
	global_store_short v[62:63], v17, off
	v_cvt_pk_bf16_f32 v17, v59, v1
	v_lshl_add_u64 v[58:59], s[14:15], 0, v[56:57]
	v_lshl_add_u64 v[56:57], s[92:93], 0, v[56:57]
	s_lshl_b64 s[0:1], s[0:1], 10
	global_store_short v[58:59], v17, off
	v_cvt_pk_bf16_f32 v17, v61, v1
	global_store_short v[56:57], v17, off
	v_or_b32_e32 v56, s0, v78
	v_mov_b32_e32 v57, s1
	s_or_b32 s0, s18, 5
	v_cvt_pk_bf16_f32 v17, v50, v1
	v_lshl_add_u64 v[58:59], s[12:13], 0, v[56:57]
	s_ashr_i32 s1, s0, 31
	global_store_short v[58:59], v17, off
	v_cvt_pk_bf16_f32 v17, v52, v1
	v_lshl_add_u64 v[58:59], s[14:15], 0, v[56:57]
	v_lshl_add_u64 v[56:57], s[92:93], 0, v[56:57]
	s_lshl_b64 s[0:1], s[0:1], 9
	global_store_short v[58:59], v17, off
	v_cvt_pk_bf16_f32 v17, v54, v1
	global_store_short v[56:57], v17, off
	v_lshl_add_u64 v[56:57], s[0:1], 0, v[164:165]
	v_cvt_pk_bf16_f32 v17, v51, v1
	v_lshlrev_b64 v[50:51], 1, v[56:57]
	s_or_b32 s0, s18, 6
	v_lshl_add_u64 v[56:57], s[12:13], 0, v[50:51]
	s_ashr_i32 s1, s0, 31
	global_store_short v[56:57], v17, off
	v_cvt_pk_bf16_f32 v17, v53, v1
	v_lshl_add_u64 v[52:53], s[14:15], 0, v[50:51]
	v_lshl_add_u64 v[50:51], s[92:93], 0, v[50:51]
	s_lshl_b64 s[0:1], s[0:1], 10
	global_store_short v[52:53], v17, off
	v_cvt_pk_bf16_f32 v17, v55, v1
	global_store_short v[50:51], v17, off
	v_or_b32_e32 v50, s0, v78
	v_mov_b32_e32 v51, s1
	s_or_b32 s0, s18, 7
	v_cvt_pk_bf16_f32 v17, v44, v1
	v_lshl_add_u64 v[52:53], s[12:13], 0, v[50:51]
	s_ashr_i32 s1, s0, 31
	global_store_short v[52:53], v17, off
	v_cvt_pk_bf16_f32 v17, v46, v1
	v_lshl_add_u64 v[52:53], s[14:15], 0, v[50:51]
	v_lshl_add_u64 v[50:51], s[92:93], 0, v[50:51]
	s_lshl_b64 s[0:1], s[0:1], 9
	global_store_short v[52:53], v17, off
	v_cvt_pk_bf16_f32 v17, v48, v1
	global_store_short v[50:51], v17, off
	v_lshl_add_u64 v[50:51], s[0:1], 0, v[164:165]
	v_cvt_pk_bf16_f32 v17, v45, v1
	v_lshlrev_b64 v[44:45], 1, v[50:51]
	s_or_b32 s0, s18, 8
	v_lshl_add_u64 v[50:51], s[12:13], 0, v[44:45]
	s_ashr_i32 s1, s0, 31
	global_store_short v[50:51], v17, off
	v_cvt_pk_bf16_f32 v17, v47, v1
	v_lshl_add_u64 v[46:47], s[14:15], 0, v[44:45]
	v_lshl_add_u64 v[44:45], s[92:93], 0, v[44:45]
	s_lshl_b64 s[0:1], s[0:1], 10
	global_store_short v[46:47], v17, off
	v_cvt_pk_bf16_f32 v17, v49, v1
	global_store_short v[44:45], v17, off
	v_or_b32_e32 v44, s0, v78
	v_mov_b32_e32 v45, s1
	s_or_b32 s0, s18, 9
	v_cvt_pk_bf16_f32 v17, v38, v1
	v_lshl_add_u64 v[46:47], s[12:13], 0, v[44:45]
	s_ashr_i32 s1, s0, 31
	global_store_short v[46:47], v17, off
	v_cvt_pk_bf16_f32 v17, v40, v1
	v_lshl_add_u64 v[46:47], s[14:15], 0, v[44:45]
	v_lshl_add_u64 v[44:45], s[92:93], 0, v[44:45]
	s_lshl_b64 s[0:1], s[0:1], 9
	global_store_short v[46:47], v17, off
	v_cvt_pk_bf16_f32 v17, v42, v1
	global_store_short v[44:45], v17, off
	v_lshl_add_u64 v[44:45], s[0:1], 0, v[164:165]
	v_cvt_pk_bf16_f32 v17, v39, v1
	v_lshlrev_b64 v[38:39], 1, v[44:45]
	s_or_b32 s0, s18, 10
	v_lshl_add_u64 v[44:45], s[12:13], 0, v[38:39]
	s_ashr_i32 s1, s0, 31
	global_store_short v[44:45], v17, off
	v_cvt_pk_bf16_f32 v17, v41, v1
	v_lshl_add_u64 v[40:41], s[14:15], 0, v[38:39]
	v_lshl_add_u64 v[38:39], s[92:93], 0, v[38:39]
	s_lshl_b64 s[0:1], s[0:1], 10
	global_store_short v[40:41], v17, off
	v_cvt_pk_bf16_f32 v17, v43, v1
	global_store_short v[38:39], v17, off
	v_or_b32_e32 v38, s0, v78
	v_mov_b32_e32 v39, s1
	s_or_b32 s0, s18, 11
	v_cvt_pk_bf16_f32 v17, v32, v1
	v_lshl_add_u64 v[40:41], s[12:13], 0, v[38:39]
	s_ashr_i32 s1, s0, 31
	global_store_short v[40:41], v17, off
	v_cvt_pk_bf16_f32 v17, v34, v1
	v_lshl_add_u64 v[40:41], s[14:15], 0, v[38:39]
	v_lshl_add_u64 v[38:39], s[92:93], 0, v[38:39]
	s_lshl_b64 s[0:1], s[0:1], 9
	global_store_short v[40:41], v17, off
	v_cvt_pk_bf16_f32 v17, v36, v1
	global_store_short v[38:39], v17, off
	v_lshl_add_u64 v[38:39], s[0:1], 0, v[164:165]
	v_cvt_pk_bf16_f32 v17, v33, v1
	v_lshlrev_b64 v[32:33], 1, v[38:39]
	s_or_b32 s0, s18, 12
	v_lshl_add_u64 v[38:39], s[12:13], 0, v[32:33]
	s_ashr_i32 s1, s0, 31
	global_store_short v[38:39], v17, off
	v_cvt_pk_bf16_f32 v17, v35, v1
	v_lshl_add_u64 v[34:35], s[14:15], 0, v[32:33]
	v_lshl_add_u64 v[32:33], s[92:93], 0, v[32:33]
	s_lshl_b64 s[0:1], s[0:1], 10
	global_store_short v[34:35], v17, off
	v_cvt_pk_bf16_f32 v17, v37, v1
	global_store_short v[32:33], v17, off
	v_or_b32_e32 v32, s0, v78
	v_mov_b32_e32 v33, s1
	s_or_b32 s0, s18, 13
	v_cvt_pk_bf16_f32 v17, v26, v1
	v_lshl_add_u64 v[34:35], s[12:13], 0, v[32:33]
	s_ashr_i32 s1, s0, 31
	global_store_short v[34:35], v17, off
	v_cvt_pk_bf16_f32 v17, v28, v1
	v_lshl_add_u64 v[34:35], s[14:15], 0, v[32:33]
	v_lshl_add_u64 v[32:33], s[92:93], 0, v[32:33]
	s_lshl_b64 s[0:1], s[0:1], 9
	global_store_short v[34:35], v17, off
	v_cvt_pk_bf16_f32 v17, v30, v1
	global_store_short v[32:33], v17, off
	v_lshl_add_u64 v[32:33], s[0:1], 0, v[164:165]
	v_cvt_pk_bf16_f32 v17, v27, v1
	v_lshlrev_b64 v[26:27], 1, v[32:33]
	s_or_b32 s0, s18, 14
	v_lshl_add_u64 v[32:33], s[12:13], 0, v[26:27]
	s_ashr_i32 s1, s0, 31
	global_store_short v[32:33], v17, off
	v_cvt_pk_bf16_f32 v17, v29, v1
	v_lshl_add_u64 v[28:29], s[14:15], 0, v[26:27]
	v_lshl_add_u64 v[26:27], s[92:93], 0, v[26:27]
	s_lshl_b64 s[0:1], s[0:1], 10
	global_store_short v[28:29], v17, off
	v_cvt_pk_bf16_f32 v17, v31, v1
	global_store_short v[26:27], v17, off
	v_or_b32_e32 v26, s0, v78
	v_mov_b32_e32 v27, s1
	s_or_b32 s0, s18, 15
	v_cvt_pk_bf16_f32 v17, v20, v1
	v_lshl_add_u64 v[28:29], s[12:13], 0, v[26:27]
	s_ashr_i32 s1, s0, 31
	global_store_short v[28:29], v17, off
	v_cvt_pk_bf16_f32 v17, v22, v1
	v_lshl_add_u64 v[28:29], s[14:15], 0, v[26:27]
	v_lshl_add_u64 v[26:27], s[92:93], 0, v[26:27]
	s_lshl_b64 s[0:1], s[0:1], 9
	global_store_short v[28:29], v17, off
	v_cvt_pk_bf16_f32 v17, v24, v1
	global_store_short v[26:27], v17, off
	v_lshl_add_u64 v[26:27], s[0:1], 0, v[164:165]
	v_cvt_pk_bf16_f32 v17, v21, v1
	v_lshlrev_b64 v[20:21], 1, v[26:27]
	v_lshl_add_u64 v[26:27], s[12:13], 0, v[20:21]
	s_add_i32 s48, s48, s30
	global_store_short v[26:27], v17, off
	v_cvt_pk_bf16_f32 v17, v23, v1
	v_lshl_add_u64 v[22:23], s[14:15], 0, v[20:21]
	v_lshl_add_u64 v[20:21], s[92:93], 0, v[20:21]
	s_cmpk_gt_i32 s48, 0x3ff
	global_store_short v[22:23], v17, off
	v_cvt_pk_bf16_f32 v17, v25, v1
	global_store_short v[20:21], v17, off
	s_barrier
	s_cbranch_scc0 .LBB0_944

.LBB0_1180:
	s_lshl_b32 s45, s44, 4
	s_mov_b32 s6, 0xffffde00
	s_mov_b32 s7, -1
	s_mov_b32 s24, 0x2200
	s_mov_b32 s25, 0
	v_lshlrev_b32_e32 v98, 1, v100
	global_load_dword v88, v[102:103], off
	global_load_dword v89, v[104:105], off
	v_or_b32_e32 v132, s45, v101
	v_mov_b64_e32 v[136:137], s[38:39]
	v_mad_i64_i32 v[136:137], s[0:1], v132, s35, v[136:137]
	v_lshl_add_u64 v[136:137], v[136:137], 0, v[98:99]
	v_lshl_add_u64 v[136:137], v[136:137], 0, s[20:21]
	v_lshl_add_u64 v[144:145], v[136:137], 0, s[6:7]
	v_lshl_add_u64 v[146:147], v[136:137], 0, s[24:25]
	global_load_ushort v148, v[136:137], off
	global_load_ushort v152, v[144:145], off
	global_load_ushort v156, v[146:147], off
	v_or_b32_e32 v133, s45, v120
	v_mov_b64_e32 v[138:139], s[38:39]
	v_mad_i64_i32 v[138:139], s[0:1], v133, s35, v[138:139]
	v_lshl_add_u64 v[138:139], v[138:139], 0, v[98:99]
	v_lshl_add_u64 v[138:139], v[138:139], 0, s[20:21]
	v_lshl_add_u64 v[144:145], v[138:139], 0, s[6:7]
	v_lshl_add_u64 v[146:147], v[138:139], 0, s[24:25]
	global_load_ushort v149, v[138:139], off
	global_load_ushort v153, v[144:145], off
	global_load_ushort v157, v[146:147], off
	v_or_b32_e32 v134, s45, v122
	v_mov_b64_e32 v[140:141], s[38:39]
	v_mad_i64_i32 v[140:141], s[0:1], v134, s35, v[140:141]
	v_lshl_add_u64 v[140:141], v[140:141], 0, v[98:99]
	v_lshl_add_u64 v[140:141], v[140:141], 0, s[20:21]
	v_lshl_add_u64 v[144:145], v[140:141], 0, s[6:7]
	v_lshl_add_u64 v[146:147], v[140:141], 0, s[24:25]
	global_load_ushort v150, v[140:141], off
	global_load_ushort v154, v[144:145], off
	global_load_ushort v158, v[146:147], off
	v_or_b32_e32 v135, s45, v123
	v_mov_b64_e32 v[142:143], s[38:39]
	v_mad_i64_i32 v[142:143], s[0:1], v135, s35, v[142:143]
	v_lshl_add_u64 v[142:143], v[142:143], 0, v[98:99]
	v_lshl_add_u64 v[142:143], v[142:143], 0, s[20:21]
	v_lshl_add_u64 v[144:145], v[142:143], 0, s[6:7]
	v_lshl_add_u64 v[146:147], v[142:143], 0, s[24:25]
	global_load_ushort v151, v[142:143], off
	global_load_ushort v155, v[144:145], off
	global_load_ushort v159, v[146:147], off
	s_waitcnt vmcnt(0)
	v_and_b32_e32 v90, v127, v132
	v_lshlrev_b32_e32 v91, 16, v148
	v_lshlrev_b32_e32 v92, 16, v152
	v_lshlrev_b32_e32 v93, 16, v156
	v_cmp_ne_u32_e32 vcc, 0, v90
	s_nop 1
	v_cndmask_b32_e32 v92, 0, v92, vcc
	v_cmp_ne_u32_e32 vcc, s40, v90
	s_nop 1
	v_cndmask_b32_e32 v93, 0, v93, vcc
	v_sub_f32_e32 v92, v92, v91
	v_sub_f32_e32 v93, v93, v91
	v_mul_f32_e32 v92, v92, v88
	v_mul_f32_e32 v93, v93, v89
	v_add_f32_e32 v92, v92, v91
	v_add_f32_e32 v92, v92, v93
	v_mul_f32_e32 v92, 0xbfb8aa3b, v92
	v_exp_f32_e32 v92, v92
	s_nop 0
	v_add_f32_e32 v95, 1.0, v92
	v_div_scale_f32 v93, s[0:1], v95, v95, 1.0
	v_rcp_f32_e32 v94, v93
	v_div_scale_f32 v112, vcc, 1.0, v95, 1.0
	v_fma_f32 v113, -v93, v94, 1.0
	v_fmac_f32_e32 v94, v113, v94
	v_mul_f32_e32 v113, v112, v94
	v_fma_f32 v114, -v93, v113, v112
	v_fmac_f32_e32 v113, v114, v94
	v_fma_f32 v93, -v93, v113, v112
	v_div_fmas_f32 v112, v93, v94, v113
	v_div_fixup_f32 v92, v112, v95, 1.0
	ds_write_b32 v109, v92
	v_and_b32_e32 v90, v127, v133
	v_lshlrev_b32_e32 v91, 16, v149
	v_lshlrev_b32_e32 v92, 16, v153
	v_lshlrev_b32_e32 v93, 16, v157
	v_cmp_ne_u32_e32 vcc, 0, v90
	s_nop 1
	v_cndmask_b32_e32 v92, 0, v92, vcc
	v_cmp_ne_u32_e32 vcc, s40, v90
	s_nop 1
	v_cndmask_b32_e32 v93, 0, v93, vcc
	v_sub_f32_e32 v92, v92, v91
	v_sub_f32_e32 v93, v93, v91
	v_mul_f32_e32 v92, v92, v88
	v_mul_f32_e32 v93, v93, v89
	v_add_f32_e32 v92, v92, v91
	v_add_f32_e32 v92, v92, v93
	v_mul_f32_e32 v92, 0xbfb8aa3b, v92
	v_exp_f32_e32 v92, v92
	s_nop 0
	v_add_f32_e32 v95, 1.0, v92
	v_div_scale_f32 v93, s[0:1], v95, v95, 1.0
	v_rcp_f32_e32 v94, v93
	v_div_scale_f32 v112, vcc, 1.0, v95, 1.0
	v_fma_f32 v113, -v93, v94, 1.0
	v_fmac_f32_e32 v94, v113, v94
	v_mul_f32_e32 v113, v112, v94
	v_fma_f32 v114, -v93, v113, v112
	v_fmac_f32_e32 v113, v114, v94
	v_fma_f32 v93, -v93, v113, v112
	v_div_fmas_f32 v112, v93, v94, v113
	v_div_fixup_f32 v92, v112, v95, 1.0
	ds_write_b32 v121, v92
	v_and_b32_e32 v90, v127, v134
	v_lshlrev_b32_e32 v91, 16, v150
	v_lshlrev_b32_e32 v92, 16, v154
	v_lshlrev_b32_e32 v93, 16, v158
	v_cmp_ne_u32_e32 vcc, 0, v90
	s_nop 1
	v_cndmask_b32_e32 v92, 0, v92, vcc
	v_cmp_ne_u32_e32 vcc, s40, v90
	s_nop 1
	v_cndmask_b32_e32 v93, 0, v93, vcc
	v_sub_f32_e32 v92, v92, v91
	v_sub_f32_e32 v93, v93, v91
	v_mul_f32_e32 v92, v92, v88
	v_mul_f32_e32 v93, v93, v89
	v_add_f32_e32 v92, v92, v91
	v_add_f32_e32 v92, v92, v93
	v_mul_f32_e32 v92, 0xbfb8aa3b, v92
	v_exp_f32_e32 v92, v92
	s_nop 0
	v_add_f32_e32 v95, 1.0, v92
	v_div_scale_f32 v93, s[0:1], v95, v95, 1.0
	v_rcp_f32_e32 v94, v93
	v_div_scale_f32 v112, vcc, 1.0, v95, 1.0
	v_fma_f32 v113, -v93, v94, 1.0
	v_fmac_f32_e32 v94, v113, v94
	v_mul_f32_e32 v113, v112, v94
	v_fma_f32 v114, -v93, v113, v112
	v_fmac_f32_e32 v113, v114, v94
	v_fma_f32 v93, -v93, v113, v112
	v_div_fmas_f32 v112, v93, v94, v113
	v_div_fixup_f32 v92, v112, v95, 1.0
	ds_write_b32 v109, v92 offset:32
	v_and_b32_e32 v90, v127, v135
	v_lshlrev_b32_e32 v91, 16, v151
	v_lshlrev_b32_e32 v92, 16, v155
	v_lshlrev_b32_e32 v93, 16, v159
	v_cmp_ne_u32_e32 vcc, 0, v90
	s_nop 1
	v_cndmask_b32_e32 v92, 0, v92, vcc
	v_cmp_ne_u32_e32 vcc, s40, v90
	s_nop 1
	v_cndmask_b32_e32 v93, 0, v93, vcc
	v_sub_f32_e32 v92, v92, v91
	v_sub_f32_e32 v93, v93, v91
	v_mul_f32_e32 v92, v92, v88
	v_mul_f32_e32 v93, v93, v89
	v_add_f32_e32 v92, v92, v91
	v_add_f32_e32 v92, v92, v93
	v_mul_f32_e32 v92, 0xbfb8aa3b, v92
	v_exp_f32_e32 v92, v92
	s_nop 0
	v_add_f32_e32 v95, 1.0, v92
	v_div_scale_f32 v93, s[0:1], v95, v95, 1.0
	v_rcp_f32_e32 v94, v93
	v_div_scale_f32 v112, vcc, 1.0, v95, 1.0
	v_fma_f32 v113, -v93, v94, 1.0
	v_fmac_f32_e32 v94, v113, v94
	v_mul_f32_e32 v113, v112, v94
	v_fma_f32 v114, -v93, v113, v112
	v_fmac_f32_e32 v113, v114, v94
	v_fma_f32 v93, -v93, v113, v112
	v_div_fmas_f32 v112, v93, v94, v113
	v_div_fixup_f32 v92, v112, v95, 1.0
	ds_write_b32 v124, v92
	v_mov_b32_e32 v88, 0
	v_mov_b32_e32 v89, 0
	v_mov_b32_e32 v90, 0
	v_mov_b32_e32 v91, 0
	v_mov_b32_e32 v92, 0
	v_mov_b32_e32 v93, 0
	v_mov_b32_e32 v94, 0
	v_mov_b32_e32 v95, 0
	v_mov_b32_e32 v112, 0
	v_mov_b32_e32 v113, 0
	v_mov_b32_e32 v114, 0
	v_mov_b32_e32 v115, 0
	v_mov_b32_e32 v116, 0
	v_mov_b32_e32 v117, 0
	v_mov_b32_e32 v118, 0
	v_mov_b32_e32 v119, 0
	s_mov_b32 s6, 0
	s_mov_b64 s[0:1], 0
	s_waitcnt lgkmcnt(0)
	s_barrier
	v_readlane_b32 s10, v255, 33
	v_readlane_b32 s11, v255, 34
	v_and_b32_e32 v151, 63, v164
	v_lshrrev_b32_e32 v152, 6, v164
	v_lshlrev_b32_e32 v148, 2, v151
	v_lshrrev_b32_e32 v153, 4, v151
	v_and_b32_e32 v154, 15, v151
	v_lshlrev_b32_e32 v149, 11, v153
	v_lshl_add_u32 v149, v152, 8, v149
	v_lshl_add_u32 v149, v154, 4, v149
	v_lshlrev_b32_e32 v150, 13, v153
	v_lshl_add_u32 v150, v152, 8, v150
	v_lshl_add_u32 v150, v154, 4, v150
	v_add_u32_e32 v150, 0x2000, v150
	global_load_dwordx4 v[136:139], v149, s[10:11]
	v_add_u32_e32 v149, 0x2000, v149
	ds_read_b32 v132, v148 offset:0
	global_load_dwordx4 v[140:143], v149, s[10:11]
	v_add_u32_e32 v149, 0x2000, v149
	ds_read_b32 v133, v148 offset:256
	global_load_dwordx4 v[144:147], v149, s[10:11]
	v_add_u32_e32 v149, 0x2000, v149
	ds_read_b32 v134, v148 offset:512
	global_load_dwordx4 v[156:159], v149, s[10:11]
	v_add_u32_e32 v149, 0x2000, v149
	ds_read_b32 v155, v148 offset:768
	global_load_dwordx4 v[160:163], v149, s[10:11]
	v_add_u32_e32 v149, 0x2000, v149
	ds_read_b32 v135, v148 offset:1024
	global_load_dwordx4 v[176:179], v149, s[10:11]
	v_add_u32_e32 v149, 0x2000, v149
	ds_read_b32 v184, v148 offset:1280
	global_load_dwordx4 v[180:183], v149, s[10:11]
	v_add_u32_e32 v149, 0x2000, v149
	ds_read_b32 v185, v148 offset:1536
	s_waitcnt vmcnt(6) lgkmcnt(6)
	v_mfma_f32_16x16x4_f32 v[88:91], v132, v136, v[88:91]
	v_mfma_f32_16x16x4_f32 v[92:95], v132, v137, v[92:95]
	v_mfma_f32_16x16x4_f32 v[112:115], v132, v138, v[112:115]
	v_mfma_f32_16x16x4_f32 v[116:119], v132, v139, v[116:119]
	global_load_dwordx4 v[136:139], v149, s[10:11]
	v_add_u32_e32 v149, 0x2000, v149
	ds_read_b32 v132, v148 offset:1792
	s_waitcnt vmcnt(6) lgkmcnt(6)
	v_mfma_f32_16x16x4_f32 v[88:91], v133, v140, v[88:91]
	v_mfma_f32_16x16x4_f32 v[92:95], v133, v141, v[92:95]
	v_mfma_f32_16x16x4_f32 v[112:115], v133, v142, v[112:115]
	v_mfma_f32_16x16x4_f32 v[116:119], v133, v143, v[116:119]
	global_load_dwordx4 v[140:143], v149, s[10:11]
	v_add_u32_e32 v149, 0x2000, v149
	ds_read_b32 v133, v148 offset:2048
	s_waitcnt vmcnt(6) lgkmcnt(6)
	v_mfma_f32_16x16x4_f32 v[88:91], v134, v144, v[88:91]
	v_mfma_f32_16x16x4_f32 v[92:95], v134, v145, v[92:95]
	v_mfma_f32_16x16x4_f32 v[112:115], v134, v146, v[112:115]
	v_mfma_f32_16x16x4_f32 v[116:119], v134, v147, v[116:119]
	global_load_dwordx4 v[144:147], v149, s[10:11]
	v_add_u32_e32 v149, 0x2000, v149
	ds_read_b32 v134, v148 offset:2304
	s_waitcnt vmcnt(6) lgkmcnt(6)
	v_mfma_f32_16x16x4_f32 v[88:91], v155, v156, v[88:91]
	v_mfma_f32_16x16x4_f32 v[92:95], v155, v157, v[92:95]
	v_mfma_f32_16x16x4_f32 v[112:115], v155, v158, v[112:115]
	v_mfma_f32_16x16x4_f32 v[116:119], v155, v159, v[116:119]
	global_load_dwordx4 v[156:159], v149, s[10:11]
	v_add_u32_e32 v149, 0x2000, v149
	ds_read_b32 v155, v148 offset:2560
	s_waitcnt vmcnt(6) lgkmcnt(6)
	v_mfma_f32_16x16x4_f32 v[88:91], v135, v160, v[88:91]
	v_mfma_f32_16x16x4_f32 v[92:95], v135, v161, v[92:95]
	v_mfma_f32_16x16x4_f32 v[112:115], v135, v162, v[112:115]
	v_mfma_f32_16x16x4_f32 v[116:119], v135, v163, v[116:119]
	global_load_dwordx4 v[160:163], v149, s[10:11]
	v_add_u32_e32 v149, 0x2000, v149
	ds_read_b32 v135, v148 offset:2816
	s_waitcnt vmcnt(6) lgkmcnt(6)
	v_mfma_f32_16x16x4_f32 v[88:91], v184, v176, v[88:91]
	v_mfma_f32_16x16x4_f32 v[92:95], v184, v177, v[92:95]
	v_mfma_f32_16x16x4_f32 v[112:115], v184, v178, v[112:115]
	v_mfma_f32_16x16x4_f32 v[116:119], v184, v179, v[116:119]
	global_load_dwordx4 v[176:179], v149, s[10:11]
	v_add_u32_e32 v149, 0x2000, v149
	ds_read_b32 v184, v148 offset:3072
	s_waitcnt vmcnt(6) lgkmcnt(6)
	v_mfma_f32_16x16x4_f32 v[88:91], v185, v180, v[88:91]
	v_mfma_f32_16x16x4_f32 v[92:95], v185, v181, v[92:95]
	v_mfma_f32_16x16x4_f32 v[112:115], v185, v182, v[112:115]
	v_mfma_f32_16x16x4_f32 v[116:119], v185, v183, v[116:119]
	global_load_dwordx4 v[180:183], v149, s[10:11]
	v_add_u32_e32 v149, 0x2000, v149
	ds_read_b32 v185, v148 offset:3328
	s_waitcnt vmcnt(6) lgkmcnt(6)
	v_mfma_f32_16x16x4_f32 v[88:91], v132, v136, v[88:91]
	v_mfma_f32_16x16x4_f32 v[92:95], v132, v137, v[92:95]
	v_mfma_f32_16x16x4_f32 v[112:115], v132, v138, v[112:115]
	v_mfma_f32_16x16x4_f32 v[116:119], v132, v139, v[116:119]
	global_load_dwordx4 v[136:139], v149, s[10:11]
	v_add_u32_e32 v149, 0x2000, v149
	ds_read_b32 v132, v148 offset:3584
	s_waitcnt vmcnt(6) lgkmcnt(6)
	v_mfma_f32_16x16x4_f32 v[88:91], v133, v140, v[88:91]
	v_mfma_f32_16x16x4_f32 v[92:95], v133, v141, v[92:95]
	v_mfma_f32_16x16x4_f32 v[112:115], v133, v142, v[112:115]
	v_mfma_f32_16x16x4_f32 v[116:119], v133, v143, v[116:119]
	global_load_dwordx4 v[140:143], v149, s[10:11]
	v_add_u32_e32 v149, 0x2000, v149
	ds_read_b32 v133, v148 offset:3840
	s_waitcnt vmcnt(6) lgkmcnt(6)
	v_mfma_f32_16x16x4_f32 v[88:91], v134, v144, v[88:91]
	v_mfma_f32_16x16x4_f32 v[92:95], v134, v145, v[92:95]
	v_mfma_f32_16x16x4_f32 v[112:115], v134, v146, v[112:115]
	v_mfma_f32_16x16x4_f32 v[116:119], v134, v147, v[116:119]
	global_load_dwordx4 v[144:147], v149, s[10:11]
	v_add_u32_e32 v149, 0x2000, v149
	ds_read_b32 v134, v148 offset:4096
	s_waitcnt vmcnt(6) lgkmcnt(6)
	v_mfma_f32_16x16x4_f32 v[88:91], v155, v156, v[88:91]
	v_mfma_f32_16x16x4_f32 v[92:95], v155, v157, v[92:95]
	v_mfma_f32_16x16x4_f32 v[112:115], v155, v158, v[112:115]
	v_mfma_f32_16x16x4_f32 v[116:119], v155, v159, v[116:119]
	global_load_dwordx4 v[156:159], v149, s[10:11]
	v_add_u32_e32 v149, 0x2000, v149
	ds_read_b32 v155, v148 offset:4352
	s_waitcnt vmcnt(6) lgkmcnt(6)
	v_mfma_f32_16x16x4_f32 v[88:91], v135, v160, v[88:91]
	v_mfma_f32_16x16x4_f32 v[92:95], v135, v161, v[92:95]
	v_mfma_f32_16x16x4_f32 v[112:115], v135, v162, v[112:115]
	v_mfma_f32_16x16x4_f32 v[116:119], v135, v163, v[116:119]
	global_load_dwordx4 v[160:163], v149, s[10:11]
	v_add_u32_e32 v149, 0x2000, v149
	ds_read_b32 v135, v148 offset:4608
	s_waitcnt vmcnt(6) lgkmcnt(6)
	v_mfma_f32_16x16x4_f32 v[88:91], v184, v176, v[88:91]
	v_mfma_f32_16x16x4_f32 v[92:95], v184, v177, v[92:95]
	v_mfma_f32_16x16x4_f32 v[112:115], v184, v178, v[112:115]
	v_mfma_f32_16x16x4_f32 v[116:119], v184, v179, v[116:119]
	global_load_dwordx4 v[176:179], v149, s[10:11]
	v_add_u32_e32 v149, 0x2000, v149
	ds_read_b32 v184, v148 offset:4864
	s_waitcnt vmcnt(6) lgkmcnt(6)
	v_mfma_f32_16x16x4_f32 v[88:91], v185, v180, v[88:91]
	v_mfma_f32_16x16x4_f32 v[92:95], v185, v181, v[92:95]
	v_mfma_f32_16x16x4_f32 v[112:115], v185, v182, v[112:115]
	v_mfma_f32_16x16x4_f32 v[116:119], v185, v183, v[116:119]
	global_load_dwordx4 v[180:183], v149, s[10:11]
	v_add_u32_e32 v149, 0x2000, v149
	ds_read_b32 v185, v148 offset:5120
	s_waitcnt vmcnt(6) lgkmcnt(6)
	v_mfma_f32_16x16x4_f32 v[88:91], v132, v136, v[88:91]
	v_mfma_f32_16x16x4_f32 v[92:95], v132, v137, v[92:95]
	v_mfma_f32_16x16x4_f32 v[112:115], v132, v138, v[112:115]
	v_mfma_f32_16x16x4_f32 v[116:119], v132, v139, v[116:119]
	global_load_dwordx4 v[136:139], v149, s[10:11]
	v_add_u32_e32 v149, 0x2000, v149
	ds_read_b32 v132, v148 offset:5376
	s_waitcnt vmcnt(6) lgkmcnt(6)
	v_mfma_f32_16x16x4_f32 v[88:91], v133, v140, v[88:91]
	v_mfma_f32_16x16x4_f32 v[92:95], v133, v141, v[92:95]
	v_mfma_f32_16x16x4_f32 v[112:115], v133, v142, v[112:115]
	v_mfma_f32_16x16x4_f32 v[116:119], v133, v143, v[116:119]
	global_load_dwordx4 v[140:143], v149, s[10:11]
	v_add_u32_e32 v149, 0x2000, v149
	ds_read_b32 v133, v148 offset:5632
	s_waitcnt vmcnt(6) lgkmcnt(6)
	v_mfma_f32_16x16x4_f32 v[88:91], v134, v144, v[88:91]
	v_mfma_f32_16x16x4_f32 v[92:95], v134, v145, v[92:95]
	v_mfma_f32_16x16x4_f32 v[112:115], v134, v146, v[112:115]
	v_mfma_f32_16x16x4_f32 v[116:119], v134, v147, v[116:119]
	global_load_dwordx4 v[144:147], v149, s[10:11]
	v_add_u32_e32 v149, 0x2000, v149
	ds_read_b32 v134, v148 offset:5888
	s_waitcnt vmcnt(6) lgkmcnt(6)
	v_mfma_f32_16x16x4_f32 v[88:91], v155, v156, v[88:91]
	v_mfma_f32_16x16x4_f32 v[92:95], v155, v157, v[92:95]
	v_mfma_f32_16x16x4_f32 v[112:115], v155, v158, v[112:115]
	v_mfma_f32_16x16x4_f32 v[116:119], v155, v159, v[116:119]
	global_load_dwordx4 v[156:159], v149, s[10:11]
	v_add_u32_e32 v149, 0x2000, v149
	ds_read_b32 v155, v148 offset:6144
	s_waitcnt vmcnt(6) lgkmcnt(6)
	v_mfma_f32_16x16x4_f32 v[88:91], v135, v160, v[88:91]
	v_mfma_f32_16x16x4_f32 v[92:95], v135, v161, v[92:95]
	v_mfma_f32_16x16x4_f32 v[112:115], v135, v162, v[112:115]
	v_mfma_f32_16x16x4_f32 v[116:119], v135, v163, v[116:119]
	global_load_dwordx4 v[160:163], v149, s[10:11]
	v_add_u32_e32 v149, 0x2000, v149
	ds_read_b32 v135, v148 offset:6400
	s_waitcnt vmcnt(6) lgkmcnt(6)
	v_mfma_f32_16x16x4_f32 v[88:91], v184, v176, v[88:91]
	v_mfma_f32_16x16x4_f32 v[92:95], v184, v177, v[92:95]
	v_mfma_f32_16x16x4_f32 v[112:115], v184, v178, v[112:115]
	v_mfma_f32_16x16x4_f32 v[116:119], v184, v179, v[116:119]
	global_load_dwordx4 v[176:179], v149, s[10:11]
	v_add_u32_e32 v149, 0x2000, v149
	ds_read_b32 v184, v148 offset:6656
	s_waitcnt vmcnt(6) lgkmcnt(6)
	v_mfma_f32_16x16x4_f32 v[88:91], v185, v180, v[88:91]
	v_mfma_f32_16x16x4_f32 v[92:95], v185, v181, v[92:95]
	v_mfma_f32_16x16x4_f32 v[112:115], v185, v182, v[112:115]
	v_mfma_f32_16x16x4_f32 v[116:119], v185, v183, v[116:119]
	global_load_dwordx4 v[180:183], v149, s[10:11]
	v_add_u32_e32 v149, 0x2000, v149
	ds_read_b32 v185, v148 offset:6912
	s_waitcnt vmcnt(6) lgkmcnt(6)
	v_mfma_f32_16x16x4_f32 v[88:91], v132, v136, v[88:91]
	v_mfma_f32_16x16x4_f32 v[92:95], v132, v137, v[92:95]
	v_mfma_f32_16x16x4_f32 v[112:115], v132, v138, v[112:115]
	v_mfma_f32_16x16x4_f32 v[116:119], v132, v139, v[116:119]
	global_load_dwordx4 v[136:139], v149, s[10:11]
	v_add_u32_e32 v149, 0x2000, v149
	ds_read_b32 v132, v148 offset:7168
	s_waitcnt vmcnt(6) lgkmcnt(6)
	v_mfma_f32_16x16x4_f32 v[88:91], v133, v140, v[88:91]
	v_mfma_f32_16x16x4_f32 v[92:95], v133, v141, v[92:95]
	v_mfma_f32_16x16x4_f32 v[112:115], v133, v142, v[112:115]
	v_mfma_f32_16x16x4_f32 v[116:119], v133, v143, v[116:119]
	global_load_dwordx4 v[140:143], v149, s[10:11]
	v_add_u32_e32 v149, 0x2000, v149
	ds_read_b32 v133, v148 offset:7424
	s_waitcnt vmcnt(6) lgkmcnt(6)
	v_mfma_f32_16x16x4_f32 v[88:91], v134, v144, v[88:91]
	v_mfma_f32_16x16x4_f32 v[92:95], v134, v145, v[92:95]
	v_mfma_f32_16x16x4_f32 v[112:115], v134, v146, v[112:115]
	v_mfma_f32_16x16x4_f32 v[116:119], v134, v147, v[116:119]
	global_load_dwordx4 v[144:147], v149, s[10:11]
	v_add_u32_e32 v149, 0x2000, v149
	ds_read_b32 v134, v148 offset:7680
	s_waitcnt vmcnt(6) lgkmcnt(6)
	v_mfma_f32_16x16x4_f32 v[88:91], v155, v156, v[88:91]
	v_mfma_f32_16x16x4_f32 v[92:95], v155, v157, v[92:95]
	v_mfma_f32_16x16x4_f32 v[112:115], v155, v158, v[112:115]
	v_mfma_f32_16x16x4_f32 v[116:119], v155, v159, v[116:119]
	global_load_dwordx4 v[156:159], v149, s[10:11]
	v_add_u32_e32 v149, 0x2000, v149
	ds_read_b32 v155, v148 offset:7936
	s_waitcnt vmcnt(6) lgkmcnt(6)
	v_mfma_f32_16x16x4_f32 v[88:91], v135, v160, v[88:91]
	v_mfma_f32_16x16x4_f32 v[92:95], v135, v161, v[92:95]
	v_mfma_f32_16x16x4_f32 v[112:115], v135, v162, v[112:115]
	v_mfma_f32_16x16x4_f32 v[116:119], v135, v163, v[116:119]
	s_waitcnt vmcnt(5) lgkmcnt(5)
	v_mfma_f32_16x16x4_f32 v[88:91], v184, v176, v[88:91]
	v_mfma_f32_16x16x4_f32 v[92:95], v184, v177, v[92:95]
	v_mfma_f32_16x16x4_f32 v[112:115], v184, v178, v[112:115]
	v_mfma_f32_16x16x4_f32 v[116:119], v184, v179, v[116:119]
	s_waitcnt vmcnt(4) lgkmcnt(4)
	v_mfma_f32_16x16x4_f32 v[88:91], v185, v180, v[88:91]
	v_mfma_f32_16x16x4_f32 v[92:95], v185, v181, v[92:95]
	v_mfma_f32_16x16x4_f32 v[112:115], v185, v182, v[112:115]
	v_mfma_f32_16x16x4_f32 v[116:119], v185, v183, v[116:119]
	s_waitcnt vmcnt(3) lgkmcnt(3)
	v_mfma_f32_16x16x4_f32 v[88:91], v132, v136, v[88:91]
	v_mfma_f32_16x16x4_f32 v[92:95], v132, v137, v[92:95]
	v_mfma_f32_16x16x4_f32 v[112:115], v132, v138, v[112:115]
	v_mfma_f32_16x16x4_f32 v[116:119], v132, v139, v[116:119]
	s_waitcnt vmcnt(2) lgkmcnt(2)
	v_mfma_f32_16x16x4_f32 v[88:91], v133, v140, v[88:91]
	v_mfma_f32_16x16x4_f32 v[92:95], v133, v141, v[92:95]
	v_mfma_f32_16x16x4_f32 v[112:115], v133, v142, v[112:115]
	v_mfma_f32_16x16x4_f32 v[116:119], v133, v143, v[116:119]
	s_waitcnt vmcnt(1) lgkmcnt(1)
	v_mfma_f32_16x16x4_f32 v[88:91], v134, v144, v[88:91]
	v_mfma_f32_16x16x4_f32 v[92:95], v134, v145, v[92:95]
	v_mfma_f32_16x16x4_f32 v[112:115], v134, v146, v[112:115]
	v_mfma_f32_16x16x4_f32 v[116:119], v134, v147, v[116:119]
	s_waitcnt vmcnt(0) lgkmcnt(0)
	v_mfma_f32_16x16x4_f32 v[88:91], v155, v156, v[88:91]
	v_mfma_f32_16x16x4_f32 v[92:95], v155, v157, v[92:95]
	v_mfma_f32_16x16x4_f32 v[112:115], v155, v158, v[112:115]
	v_mfma_f32_16x16x4_f32 v[116:119], v155, v159, v[116:119]
	s_nop 15
	s_nop 3
	s_mov_b32 s46, 0
	s_mov_b64 s[24:25], -1
	ds_write_b32 v150, v88 offset:0
	ds_write_b32 v150, v89 offset:2048
	ds_write_b32 v150, v90 offset:4096
	ds_write_b32 v150, v91 offset:6144
	ds_write_b32 v150, v92 offset:4
	ds_write_b32 v150, v93 offset:2052
	ds_write_b32 v150, v94 offset:4100
	ds_write_b32 v150, v95 offset:6148
	ds_write_b32 v150, v112 offset:8
	ds_write_b32 v150, v113 offset:2056
	ds_write_b32 v150, v114 offset:4104
	ds_write_b32 v150, v115 offset:6152
	ds_write_b32 v150, v116 offset:12
	ds_write_b32 v150, v117 offset:2060
	ds_write_b32 v150, v118 offset:4108
	ds_write_b32 v150, v119 offset:6156
	s_waitcnt lgkmcnt(0)
	s_barrier
